# ssd_p1 B/X conv loops and ssd_p3 X conv loop: lanes remapped to 16 tokens x 4 channel groups per wave (4x fewer cache lines per gather load)
# baseline (speedup 1.0000x reference)
; #define LAS __attribute__((address_space(3)))
; DI f32x4 zero4() { float a, b, c, d; asm volatile("v_mov_b32 %0, 0\n\tv_mov_b32 %1, 0\n\tv_mov_b32 %2, 0\n\tv_mov_b32 %3, 0\n\ts_nop 1" : "=v"(a), "=v"(b), "=v"(c), "=v"(d)); return (f32x4){a, b, c, d}; }
; DI unsigned char* WSP(const Params& p) { GAS unsigned char* w = (GAS unsigned char*)p.ws; asm volatile("" : "+s"(w)); return (unsigned char*)w; }
; DI unsigned pk2(float lo, float hi) { f32x2 v = {lo, hi}; bf16v2 b = __builtin_convertvector(v, bf16v2); return __builtin_bit_cast(unsigned, b); }
; DI void ssd_p3_item(const Params& p, int L, int item, LAS unsigned char* lds, int tid) {
;     ...
;     for (int i0 = 0; i0 < 8; i0 += 4) {
;         f32x4 sa[4], sb2[4];
; #pragma unroll
;         for (int i = 0; i < 4; ++i) { const int u = tid + 512 * (i0 + i), hx = u >> 10, rem = u & 1023, pp = rem >> 4, n0 = (rem & 15) * 8;
;             const float* st = (const float*)(WSP(p) + WS_STATES) + ((size_t)((b * 8 + g * 4 + hx) * 32 + c)) * 8192 + pp * 128 + n0;
;             sa[i] = *(const f32x4*)st; sb2[i] = *(const f32x4*)(st + 4); }
;         __builtin_amdgcn_sched_barrier(0);
; #pragma unroll
;         for (int i = 0; i < 4; ++i) { const int u = tid + 512 * (i0 + i), hx = u >> 10, rem = u & 1023, pp = rem >> 4, n0 = (rem & 15) * 8;
;             *(LAS u32x4*)(Sb + (hx * 64 + pp) * 136 + n0) = (u32x4){pk2(sa[i].x, sa[i].y), pk2(sa[i].z, sa[i].w), pk2(sb2[i].x, sb2[i].y), pk2(sb2[i].z, sb2[i].w)}; }
;     }
;     __syncthreads();
;     f32x4 y[4][4];
; #pragma unroll
;     for (int hx = 0; hx < 4; ++hx) {
;         const float el = __expf(acs[hx * 128 + w * 16 + i16]);
; #pragma unroll
;         for (int pt = 0; pt < 4; ++pt) { f32x4 a4 = zero4();
; #pragma unroll
;             for (int kk = 0; kk < 4; ++kk) { const bf16x8 av = *(const LAS bf16x8*)(Sb + (hx * 64 + pt * 16 + i16) * 136 + kk * 32 + quad * 8);
;                 a4 = __builtin_amdgcn_mfma_f32_16x16x32_bf16(av, cfr[kk], a4, 0, 0, 0); }
;             y[hx][pt] = a4 * el; }
.LBB0_433:
	v_add_u32_e32 v65, s9, v232
	v_ashrrev_i32_e32 v27, 10, v65
	v_add_u32_e32 v27, s8, v27
	v_lshl_or_b32 v36, v27, 5, s5
	v_ashrrev_i32_e32 v37, 31, v36
	s_mov_b64 s[10:11], s[28:29]
	v_lshlrev_b64 v[36:37], 15, v[36:37]
	v_add_u32_e32 v84, 0x200, v65
	v_ashrrev_i32_e32 v52, 10, v84
	v_lshl_add_u64 v[36:37], s[10:11], 0, v[36:37]
	v_lshl_add_u64 v[36:37], v[36:37], 0, v[198:199]
	v_mov_b32_e32 v27, v199
	v_add_u32_e32 v52, s8, v52
	v_lshl_add_u64 v[36:37], v[36:37], 0, v[26:27]
	v_lshl_or_b32 v52, v52, 5, s5
	v_lshl_add_u64 v[48:49], v[36:37], 0, s[70:71]
	v_add_co_u32_e32 v36, vcc, s69, v36
	v_ashrrev_i32_e32 v53, 31, v52
	s_nop 0
	v_addc_co_u32_e32 v37, vcc, 0, v37, vcc
	s_mov_b64 s[10:11], s[28:29]
	v_lshlrev_b64 v[52:53], 15, v[52:53]
	v_lshlrev_b32_e32 v54, 5, v84
	v_add_u32_e32 v85, 0x400, v65
	global_load_dwordx4 v[36:39], v[36:37], off
	s_nop 0
	global_load_dwordx4 v[48:51], v[48:49], off offset:16
	v_and_b32_e32 v54, 0x7e00, v54
	v_lshl_add_u64 v[52:53], s[10:11], 0, v[52:53]
	v_mov_b32_e32 v55, v199
	v_ashrrev_i32_e32 v60, 10, v85
	v_lshl_add_u64 v[52:53], v[52:53], 0, v[54:55]
	v_add_u32_e32 v60, s8, v60
	v_lshl_add_u64 v[52:53], v[52:53], 0, v[26:27]
	v_lshl_or_b32 v60, v60, 5, s5
	v_lshl_add_u64 v[56:57], v[52:53], 0, s[70:71]
	v_add_co_u32_e32 v52, vcc, s69, v52
	v_ashrrev_i32_e32 v61, 31, v60
	s_nop 0
	v_addc_co_u32_e32 v53, vcc, 0, v53, vcc
	s_mov_b64 s[10:11], s[28:29]
	v_lshlrev_b64 v[60:61], 15, v[60:61]
	v_add_u32_e32 v86, 0x600, v65
	global_load_dwordx4 v[52:55], v[52:53], off
	s_nop 0
	global_load_dwordx4 v[56:59], v[56:57], off offset:16
	v_ashrrev_i32_e32 v70, 10, v86
	v_lshl_add_u64 v[60:61], s[10:11], 0, v[60:61]
	v_lshl_add_u64 v[60:61], v[60:61], 0, v[198:199]
	v_add_u32_e32 v70, s8, v70
	v_lshl_add_u64 v[60:61], v[60:61], 0, v[26:27]
	v_lshl_or_b32 v70, v70, 5, s5
	v_lshl_add_u64 v[66:67], v[60:61], 0, s[70:71]
	v_add_co_u32_e32 v60, vcc, s69, v60
	v_ashrrev_i32_e32 v71, 31, v70
	s_nop 0
	v_addc_co_u32_e32 v61, vcc, 0, v61, vcc
	s_mov_b64 s[10:11], s[28:29]
	v_lshlrev_b64 v[70:71], 15, v[70:71]
	v_lshlrev_b32_e32 v72, 5, v86
	global_load_dwordx4 v[60:63], v[60:61], off
	s_nop 0
	global_load_dwordx4 v[66:69], v[66:67], off offset:16
	v_and_b32_e32 v72, 0x7e00, v72
	v_lshl_add_u64 v[70:71], s[10:11], 0, v[70:71]
	v_mov_b32_e32 v73, v199
	v_lshl_add_u64 v[70:71], v[70:71], 0, v[72:73]
	v_lshl_add_u64 v[70:71], v[70:71], 0, v[26:27]
	v_lshl_add_u64 v[74:75], v[70:71], 0, s[70:71]
	v_add_co_u32_e32 v70, vcc, s69, v70
	s_nop 1
	v_addc_co_u32_e32 v71, vcc, 0, v71, vcc
	global_load_dwordx4 v[70:73], v[70:71], off
	s_nop 0
	global_load_dwordx4 v[80:83], v[74:75], off offset:16
	v_lshrrev_b32_e32 v27, 4, v65
	v_and_or_b32 v27, v27, s27, v25
	s_waitcnt vmcnt(7)
	v_cvt_pk_bf16_f32 v36, v36, v37
	v_cvt_pk_bf16_f32 v37, v38, v39
	s_waitcnt vmcnt(6)
	v_cvt_pk_bf16_f32 v38, v48, v49
	v_cvt_pk_bf16_f32 v39, v50, v51
	v_mad_u64_u32 v[48:49], s[10:11], v27, s68, v[24:25]
	v_lshrrev_b32_e32 v27, 4, v84
	ds_write_b128 v48, v[36:39] offset:34816
	v_mad_u64_u32 v[48:49], s[10:11], v27, s68, v[24:25]
	v_lshrrev_b32_e32 v27, 4, v85
	s_waitcnt vmcnt(5)
	v_cvt_pk_bf16_f32 v36, v52, v53
	v_cvt_pk_bf16_f32 v37, v54, v55
	s_waitcnt vmcnt(4)
	v_cvt_pk_bf16_f32 v38, v56, v57
	v_cvt_pk_bf16_f32 v39, v58, v59
	v_and_or_b32 v27, v27, s27, v25
	ds_write_b128 v48, v[36:39] offset:34816
	s_waitcnt vmcnt(3)
	v_cvt_pk_bf16_f32 v36, v60, v61
	v_cvt_pk_bf16_f32 v37, v62, v63
	s_waitcnt vmcnt(2)
	v_cvt_pk_bf16_f32 v38, v66, v67
	v_cvt_pk_bf16_f32 v39, v68, v69
	v_mad_u64_u32 v[48:49], s[10:11], v27, s68, v[24:25]
	v_lshrrev_b32_e32 v27, 4, v86
	ds_write_b128 v48, v[36:39] offset:34816
	s_waitcnt vmcnt(1)
	v_cvt_pk_bf16_f32 v36, v70, v71
	v_cvt_pk_bf16_f32 v37, v72, v73
	s_waitcnt vmcnt(0)
	v_cvt_pk_bf16_f32 v38, v80, v81
	v_cvt_pk_bf16_f32 v39, v82, v83
	v_mad_u64_u32 v[48:49], s[10:11], v27, s68, v[24:25]
	s_movk_i32 s9, 0x800
	s_andn2_b64 vcc, exec, s[6:7]
	s_mov_b64 s[6:7], 0
	ds_write_b128 v48, v[36:39] offset:34816
	s_cbranch_vccz .LBB0_433
	s_andn2_b32 s54, s54, 63
	s_add_i32 s5, s54, 0
	v_lshl_add_u32 v24, v234, 2, s5
	v_add_u32_e32 v65, 0x23000, v24
	s_waitcnt lgkmcnt(0)
	s_barrier
	ds_read_b32 v24, v65
	v_add_u32_e32 v74, 0x8800, v64
	v_add_u32_e32 v75, 0x9900, v64
	v_add_u32_e32 v96, 0xaa00, v64
	v_add_u32_e32 v100, 0xbb00, v64
	s_waitcnt lgkmcnt(0)
	v_mul_f32_e32 v24, 0x3fb8aa3b, v24
	v_exp_f32_e32 v116, v24
	v_mov_b32 v24, 0
	v_mov_b32 v25, 0
	v_mov_b32 v26, 0
	v_mov_b32 v27, 0
	s_nop 1
	ds_read_b128 v[36:39], v64 offset:34816
	v_add_u32_e32 v118, 0xcc00, v64
	v_add_u32_e32 v119, 0xdd00, v64
	v_add_u32_e32 v122, 0xee00, v64
	s_waitcnt lgkmcnt(0)
	v_mfma_f32_16x16x32_bf16 v[24:27], v[36:39], v[104:107], v[24:27]
	ds_read_b128 v[36:39], v64 offset:34880
	v_add_u32_e32 v126, 0xff00, v64
	s_mov_b64 s[82:83], 0x1830
	s_waitcnt lgkmcnt(0)
	v_mfma_f32_16x16x32_bf16 v[24:27], v[36:39], v[76:79], v[24:27]
	ds_read_b128 v[36:39], v64 offset:34944
	v_mul_u32_u24_e32 v111, 0x110, v234
	v_cmp_lt_u32_e64 s[6:7], 2, v117
	s_waitcnt lgkmcnt(0)
	v_mfma_f32_16x16x32_bf16 v[24:27], v[36:39], v[44:47], v[24:27]
	ds_read_b128 v[36:39], v64 offset:35008
	v_cmp_lt_u32_e64 s[8:9], 1, v117
	s_mov_b32 s5, 0
	s_waitcnt lgkmcnt(0)
	v_mfma_f32_16x16x32_bf16 v[24:27], v[36:39], v[40:43], v[24:27]
	v_mov_b32 v36, 0
	v_mov_b32 v37, 0
	v_mov_b32 v38, 0
	v_mov_b32 v39, 0
	s_nop 1
	ds_read_b128 v[48:51], v64 offset:39168
	v_cmp_ne_u32_e64 s[10:11], 0, v117
	s_waitcnt lgkmcnt(0)
	v_mfma_f32_16x16x32_bf16 v[36:39], v[48:51], v[104:107], v[36:39]
	ds_read_b128 v[48:51], v64 offset:39232
	s_waitcnt lgkmcnt(0)
; #define LAS __attribute__((address_space(3)))
; DI f32x4 zero4() { float a, b, c, d; asm volatile("v_mov_b32 %0, 0\n\tv_mov_b32 %1, 0\n\tv_mov_b32 %2, 0\n\tv_mov_b32 %3, 0\n\ts_nop 1" : "=v"(a), "=v"(b), "=v"(c), "=v"(d)); return (f32x4){a, b, c, d}; }
; DI void ssd_p3_item(const Params& p, int L, int item, LAS unsigned char* lds, int tid) {
;     ...
;     f32x4 y[4][4];
; #pragma unroll
;     for (int hx = 0; hx < 4; ++hx) {
;         const float el = __expf(acs[hx * 128 + w * 16 + i16]);
; #pragma unroll
;         for (int pt = 0; pt < 4; ++pt) { f32x4 a4 = zero4();
; #pragma unroll
;             for (int kk = 0; kk < 4; ++kk) { const bf16x8 av = *(const LAS bf16x8*)(Sb + (hx * 64 + pt * 16 + i16) * 136 + kk * 32 + quad * 8);
;                 a4 = __builtin_amdgcn_mfma_f32_16x16x32_bf16(av, cfr[kk], a4, 0, 0, 0); }
;             y[hx][pt] = a4 * el; }
;     }
	v_mfma_f32_16x16x32_bf16 v[36:39], v[48:51], v[76:79], v[36:39]
	ds_read_b128 v[48:51], v64 offset:39296
	s_waitcnt lgkmcnt(0)
	v_mfma_f32_16x16x32_bf16 v[36:39], v[48:51], v[44:47], v[36:39]
	ds_read_b128 v[48:51], v64 offset:39360
	s_waitcnt lgkmcnt(0)
	v_mfma_f32_16x16x32_bf16 v[36:39], v[48:51], v[40:43], v[36:39]
	v_mov_b32 v48, 0
	v_mov_b32 v49, 0
	v_mov_b32 v50, 0
	v_mov_b32 v51, 0
	s_nop 1
	ds_read_b128 v[52:55], v64 offset:43520
	s_waitcnt lgkmcnt(0)
	v_mfma_f32_16x16x32_bf16 v[48:51], v[52:55], v[104:107], v[48:51]
	ds_read_b128 v[52:55], v64 offset:43584
	s_waitcnt lgkmcnt(0)
	v_mfma_f32_16x16x32_bf16 v[48:51], v[52:55], v[76:79], v[48:51]
	ds_read_b128 v[52:55], v64 offset:43648
	s_waitcnt lgkmcnt(0)
	v_mfma_f32_16x16x32_bf16 v[48:51], v[52:55], v[44:47], v[48:51]
	ds_read_b128 v[52:55], v64 offset:43712
	s_waitcnt lgkmcnt(0)
	v_mfma_f32_16x16x32_bf16 v[56:59], v[52:55], v[40:43], v[48:51]
	v_mov_b32 v48, 0
	v_mov_b32 v49, 0
	v_mov_b32 v50, 0
	v_mov_b32 v51, 0
	s_nop 1
	ds_read_b128 v[52:55], v64 offset:47872
	s_waitcnt lgkmcnt(0)
	v_mfma_f32_16x16x32_bf16 v[48:51], v[52:55], v[104:107], v[48:51]
	ds_read_b128 v[52:55], v64 offset:47936
	s_waitcnt lgkmcnt(0)
	v_mfma_f32_16x16x32_bf16 v[48:51], v[52:55], v[76:79], v[48:51]
	ds_read_b128 v[52:55], v64 offset:48000
	s_waitcnt lgkmcnt(0)
	v_mfma_f32_16x16x32_bf16 v[48:51], v[52:55], v[44:47], v[48:51]
	ds_read_b128 v[52:55], v64 offset:48064
	s_waitcnt lgkmcnt(0)
	v_mfma_f32_16x16x32_bf16 v[60:63], v[52:55], v[40:43], v[48:51]
	s_nop 4
	ds_read_b32 v48, v65 offset:512
	s_waitcnt lgkmcnt(0)
	v_mul_f32_e32 v48, 0x3fb8aa3b, v48
	v_exp_f32_e32 v114, v48
	v_mov_b32 v48, 0
	v_mov_b32 v49, 0
	v_mov_b32 v50, 0
	v_mov_b32 v51, 0
	s_nop 1
	ds_read_b128 v[52:55], v64 offset:52224
	s_waitcnt lgkmcnt(0)
	v_mfma_f32_16x16x32_bf16 v[48:51], v[52:55], v[104:107], v[48:51]
	ds_read_b128 v[52:55], v64 offset:52288
	s_waitcnt lgkmcnt(0)
	v_mfma_f32_16x16x32_bf16 v[48:51], v[52:55], v[76:79], v[48:51]
	ds_read_b128 v[52:55], v64 offset:52352
	s_waitcnt lgkmcnt(0)
	v_mfma_f32_16x16x32_bf16 v[48:51], v[52:55], v[44:47], v[48:51]
	ds_read_b128 v[52:55], v64 offset:52416
	s_waitcnt lgkmcnt(0)
	v_mfma_f32_16x16x32_bf16 v[48:51], v[52:55], v[40:43], v[48:51]
	v_mov_b32 v52, 0
	v_mov_b32 v53, 0
	v_mov_b32 v54, 0
	v_mov_b32 v55, 0
	s_nop 1
	ds_read_b128 v[66:69], v64 offset:56576
	s_waitcnt lgkmcnt(0)
	v_mfma_f32_16x16x32_bf16 v[52:55], v[66:69], v[104:107], v[52:55]
	ds_read_b128 v[66:69], v64 offset:56640
	s_waitcnt lgkmcnt(0)
	v_mfma_f32_16x16x32_bf16 v[52:55], v[66:69], v[76:79], v[52:55]
	ds_read_b128 v[66:69], v64 offset:56704
	s_waitcnt lgkmcnt(0)
	v_mfma_f32_16x16x32_bf16 v[52:55], v[66:69], v[44:47], v[52:55]
	ds_read_b128 v[66:69], v64 offset:56768
	s_waitcnt lgkmcnt(0)
	v_mfma_f32_16x16x32_bf16 v[52:55], v[66:69], v[40:43], v[52:55]
	v_mov_b32 v66, 0
	v_mov_b32 v67, 0
	v_mov_b32 v68, 0
	v_mov_b32 v69, 0
	s_nop 1
	ds_read_b128 v[70:73], v64 offset:60928
	s_waitcnt lgkmcnt(0)
	v_mfma_f32_16x16x32_bf16 v[66:69], v[70:73], v[104:107], v[66:69]
	ds_read_b128 v[70:73], v64 offset:60992
	s_waitcnt lgkmcnt(0)
	v_mfma_f32_16x16x32_bf16 v[66:69], v[70:73], v[76:79], v[66:69]
	ds_read_b128 v[70:73], v64 offset:61056
	s_waitcnt lgkmcnt(0)
	v_mfma_f32_16x16x32_bf16 v[66:69], v[70:73], v[44:47], v[66:69]
	ds_read_b128 v[70:73], v64 offset:61120
	s_waitcnt lgkmcnt(0)
	v_mfma_f32_16x16x32_bf16 v[88:91], v[70:73], v[40:43], v[66:69]
	v_mov_b32 v66, 0
	v_mov_b32 v67, 0
	v_mov_b32 v68, 0
	v_mov_b32 v69, 0
	s_nop 1
	ds_read_b128 v[70:73], v64 offset:65280
	s_waitcnt lgkmcnt(0)
	v_mfma_f32_16x16x32_bf16 v[66:69], v[70:73], v[104:107], v[66:69]
	ds_read_b128 v[70:73], v64 offset:65344
	s_waitcnt lgkmcnt(0)
	v_mfma_f32_16x16x32_bf16 v[66:69], v[70:73], v[76:79], v[66:69]
	ds_read_b128 v[70:73], v64 offset:65408
	s_waitcnt lgkmcnt(0)
	v_mfma_f32_16x16x32_bf16 v[66:69], v[70:73], v[44:47], v[66:69]
	ds_read_b128 v[70:73], v64 offset:65472
	ds_read_b32 v64, v65 offset:1024
	s_waitcnt lgkmcnt(0)
	v_mul_f32_e32 v64, 0x3fb8aa3b, v64
	v_mfma_f32_16x16x32_bf16 v[92:95], v[70:73], v[40:43], v[66:69]
	v_mov_b32 v66, 0
	v_mov_b32 v67, 0
	v_mov_b32 v68, 0
	v_mov_b32 v69, 0
	s_nop 1
	ds_read_b128 v[70:73], v74 offset:34816
	v_exp_f32_e32 v110, v64
	s_waitcnt lgkmcnt(0)
	v_mfma_f32_16x16x32_bf16 v[66:69], v[70:73], v[104:107], v[66:69]
	ds_read_b128 v[70:73], v74 offset:34880
	s_waitcnt lgkmcnt(0)
	v_mfma_f32_16x16x32_bf16 v[66:69], v[70:73], v[76:79], v[66:69]
	ds_read_b128 v[70:73], v74 offset:34944
	s_waitcnt lgkmcnt(0)
	v_mfma_f32_16x16x32_bf16 v[66:69], v[70:73], v[44:47], v[66:69]
	ds_read_b128 v[70:73], v74 offset:35008
	s_waitcnt lgkmcnt(0)
	v_mfma_f32_16x16x32_bf16 v[80:83], v[70:73], v[40:43], v[66:69]
	v_mov_b32 v66, 0
	v_mov_b32 v67, 0
	v_mov_b32 v68, 0
	v_mov_b32 v69, 0
	s_nop 1
	ds_read_b128 v[70:73], v75 offset:34816
	s_waitcnt lgkmcnt(0)
	v_mfma_f32_16x16x32_bf16 v[66:69], v[70:73], v[104:107], v[66:69]
	ds_read_b128 v[70:73], v75 offset:34880
	s_waitcnt lgkmcnt(0)
	v_mfma_f32_16x16x32_bf16 v[66:69], v[70:73], v[76:79], v[66:69]
	ds_read_b128 v[70:73], v75 offset:34944
	s_waitcnt lgkmcnt(0)
; #define LAS __attribute__((address_space(3)))
; DI f32x4 zero4() { float a, b, c, d; asm volatile("v_mov_b32 %0, 0\n\tv_mov_b32 %1, 0\n\tv_mov_b32 %2, 0\n\tv_mov_b32 %3, 0\n\ts_nop 1" : "=v"(a), "=v"(b), "=v"(c), "=v"(d)); return (f32x4){a, b, c, d}; }
; DI void ssd_p3_item(const Params& p, int L, int item, LAS unsigned char* lds, int tid) {
;     ...
;         for (int pt = 0; pt < 4; ++pt) { f32x4 a4 = zero4();
; #pragma unroll
;             for (int kk = 0; kk < 4; ++kk) { const bf16x8 av = *(const LAS bf16x8*)(Sb + (hx * 64 + pt * 16 + i16) * 136 + kk * 32 + quad * 8);
;                 a4 = __builtin_amdgcn_mfma_f32_16x16x32_bf16(av, cfr[kk], a4, 0, 0, 0); }
;             y[hx][pt] = a4 * el; }
;     }
;     __syncthreads();
; #pragma unroll 1
;     for (int i = 0; i < 8; ++i) { const int u = tid + 512 * i, l = u & 127, rest = u >> 7, hx = rest >> 3, ch = (rest & 7) * 8; float o[8];
;         conv8(proj, b, c * 128 + l, (g * 4 + hx) * 64 + ch, cw, cb, o);
	v_mfma_f32_16x16x32_bf16 v[66:69], v[70:73], v[44:47], v[66:69]
	ds_read_b128 v[70:73], v75 offset:35008
	s_waitcnt lgkmcnt(0)
	v_mfma_f32_16x16x32_bf16 v[84:87], v[70:73], v[40:43], v[66:69]
	v_mov_b32 v66, 0
	v_mov_b32 v67, 0
	v_mov_b32 v68, 0
	v_mov_b32 v69, 0
	s_nop 1
	ds_read_b128 v[70:73], v96 offset:34816
	s_waitcnt lgkmcnt(0)
	v_mfma_f32_16x16x32_bf16 v[66:69], v[70:73], v[104:107], v[66:69]
	ds_read_b128 v[70:73], v96 offset:34880
	s_waitcnt lgkmcnt(0)
	v_mfma_f32_16x16x32_bf16 v[66:69], v[70:73], v[76:79], v[66:69]
	ds_read_b128 v[70:73], v96 offset:34944
	s_waitcnt lgkmcnt(0)
	v_mfma_f32_16x16x32_bf16 v[66:69], v[70:73], v[44:47], v[66:69]
	ds_read_b128 v[70:73], v96 offset:35008
	s_waitcnt lgkmcnt(0)
	v_mfma_f32_16x16x32_bf16 v[96:99], v[70:73], v[40:43], v[66:69]
	v_mov_b32 v66, 0
	v_mov_b32 v67, 0
	v_mov_b32 v68, 0
	v_mov_b32 v69, 0
	s_nop 1
	ds_read_b128 v[70:73], v100 offset:34816
	ds_read_b32 v64, v65 offset:1536
	s_waitcnt lgkmcnt(1)
	v_mfma_f32_16x16x32_bf16 v[66:69], v[70:73], v[104:107], v[66:69]
	ds_read_b128 v[70:73], v100 offset:34880
	s_waitcnt lgkmcnt(1)
	v_mul_f32_e32 v64, 0x3fb8aa3b, v64
	v_exp_f32_e32 v108, v64
	s_waitcnt lgkmcnt(0)
	v_mfma_f32_16x16x32_bf16 v[66:69], v[70:73], v[76:79], v[66:69]
	ds_read_b128 v[70:73], v100 offset:34944
	s_waitcnt lgkmcnt(0)
	v_mfma_f32_16x16x32_bf16 v[66:69], v[70:73], v[44:47], v[66:69]
	ds_read_b128 v[70:73], v100 offset:35008
	s_waitcnt lgkmcnt(0)
	v_mfma_f32_16x16x32_bf16 v[100:103], v[70:73], v[40:43], v[66:69]
	v_mov_b32 v64, 0
	v_mov_b32 v65, 0
	v_mov_b32 v66, 0
	v_mov_b32 v67, 0
	s_nop 1
	s_nop 4
	ds_read_b128 v[68:71], v118 offset:34816
	s_waitcnt lgkmcnt(0)
	v_mfma_f32_16x16x32_bf16 v[64:67], v[68:71], v[104:107], v[64:67]
	ds_read_b128 v[68:71], v118 offset:34880
	s_waitcnt lgkmcnt(0)
	v_mfma_f32_16x16x32_bf16 v[64:67], v[68:71], v[76:79], v[64:67]
	ds_read_b128 v[68:71], v118 offset:34944
	s_waitcnt lgkmcnt(0)
	v_mfma_f32_16x16x32_bf16 v[64:67], v[68:71], v[44:47], v[64:67]
	ds_read_b128 v[68:71], v118 offset:35008
	s_waitcnt lgkmcnt(0)
	v_mfma_f32_16x16x32_bf16 v[64:67], v[68:71], v[40:43], v[64:67]
	v_mov_b32 v68, 0
	v_mov_b32 v69, 0
	v_mov_b32 v70, 0
	v_mov_b32 v71, 0
	s_nop 1
	ds_read_b128 v[72:75], v119 offset:34816
	s_waitcnt lgkmcnt(0)
	v_mfma_f32_16x16x32_bf16 v[68:71], v[72:75], v[104:107], v[68:71]
	ds_read_b128 v[72:75], v119 offset:34880
	s_waitcnt lgkmcnt(0)
	v_mfma_f32_16x16x32_bf16 v[68:71], v[72:75], v[76:79], v[68:71]
	ds_read_b128 v[72:75], v119 offset:34944
	s_waitcnt lgkmcnt(0)
	v_mfma_f32_16x16x32_bf16 v[68:71], v[72:75], v[44:47], v[68:71]
	ds_read_b128 v[72:75], v119 offset:35008
	s_waitcnt lgkmcnt(0)
	v_mfma_f32_16x16x32_bf16 v[68:71], v[72:75], v[40:43], v[68:71]
	v_mov_b32 v72, 0
	v_mov_b32 v73, 0
	v_mov_b32 v74, 0
	v_mov_b32 v75, 0
	s_nop 1
	ds_read_b128 v[118:121], v122 offset:34816
	s_waitcnt lgkmcnt(0)
	v_mfma_f32_16x16x32_bf16 v[72:75], v[118:121], v[104:107], v[72:75]
	ds_read_b128 v[118:121], v122 offset:34880
	s_waitcnt lgkmcnt(0)
	v_mfma_f32_16x16x32_bf16 v[72:75], v[118:121], v[76:79], v[72:75]
	ds_read_b128 v[118:121], v122 offset:34944
	s_waitcnt lgkmcnt(0)
	v_mfma_f32_16x16x32_bf16 v[72:75], v[118:121], v[44:47], v[72:75]
	ds_read_b128 v[118:121], v122 offset:35008
	s_waitcnt lgkmcnt(0)
	v_mfma_f32_16x16x32_bf16 v[72:75], v[118:121], v[40:43], v[72:75]
	v_mov_b32 v118, 0
	v_mov_b32 v119, 0
	v_mov_b32 v120, 0
	v_mov_b32 v121, 0
	s_nop 1
	ds_read_b128 v[122:125], v126 offset:34816
	s_waitcnt lgkmcnt(0)
	v_mfma_f32_16x16x32_bf16 v[104:107], v[122:125], v[104:107], v[118:121]
	s_nop 2
	ds_read_b128 v[118:121], v126 offset:34880
	s_waitcnt lgkmcnt(0)
	v_mfma_f32_16x16x32_bf16 v[76:79], v[118:121], v[76:79], v[104:107]
	s_nop 2
	ds_read_b128 v[104:107], v126 offset:34944
	v_lshl_add_u32 v120, v115, 1, 0
	s_waitcnt lgkmcnt(0)
	v_mfma_f32_16x16x32_bf16 v[44:47], v[104:107], v[44:47], v[76:79]
	s_nop 2
	ds_read_b128 v[76:79], v126 offset:35008
	v_lshl_add_u64 v[104:105], v[112:113], 0, s[82:83]
	s_waitcnt lgkmcnt(0)
	v_mfma_f32_16x16x32_bf16 v[76:79], v[76:79], v[40:43], v[44:47]
	v_lshrrev_b32_e32 v140, 2, v232
	v_sub_u32_e32 v117, v117, v115
	v_add_u32_e32 v117, v117, v140
	v_lshl_add_u32 v120, v140, 1, 0
	v_and_b32_e32 v141, 3, v232
	v_lshlrev_b32_e32 v141, 7, v141
	v_cmp_lt_u32_e64 s[6:7], 2, v117
	v_cmp_lt_u32_e64 s[8:9], 1, v117
	v_cmp_ne_u32_e64 s[10:11], 0, v117
	v_add3_u32 v42, s56, 1, v117
	v_mov_b64_e32 v[40:41], s[22:23]
	v_mad_i64_i32 v[42:43], s[100:101], v42, s96, v[40:41]
	v_lshl_add_u64 v[104:105], v[42:43], 0, s[82:83]
	v_add_u32_e32 v42, s80, v117
	v_mov_b64_e32 v[40:41], s[22:23]
	v_mad_i64_i32 v[42:43], s[54:55], v42, s96, v[40:41]
	v_lshl_add_u64 v[106:107], v[42:43], 0, s[82:83]
	v_add_u32_e32 v42, s57, v117
	v_mad_i64_i32 v[42:43], s[54:55], v42, s96, v[40:41]
	v_lshl_add_u64 v[112:113], v[42:43], 0, s[82:83]
	v_add_u32_e32 v42, s56, v117
	v_mad_i64_i32 v[40:41], s[54:55], v42, s96, v[40:41]
	v_lshl_add_u64 v[118:119], v[40:41], 0, s[82:83]
	s_barrier
	s_branch .LBB0_436

; DI float bflo(unsigned v) { return __uint_as_float(v << 16); }
; DI float bfhi(unsigned v) { return __uint_as_float(v & 0xffff0000u); }
; DI void conv8(const bf16_t* proj, int b, int t, int chx, const float* cw, const float* cbias, float (&o)[8]) {
;     const f32x4 b0 = *(const f32x4*)(cbias + chx), b1 = *(const f32x4*)(cbias + chx + 4);
;     float a[8] = {b0.x, b0.y, b0.z, b0.w, b1.x, b1.y, b1.z, b1.w};
; #pragma unroll
;     for (int k = 0; k < 4; ++k) { const int tt = t - 3 + k;
;         if (tt >= 0) { const u32x4 v = *(const u32x4*)(proj + (size_t)(b * T + tt) * NINP + C_XBC + chx);
;             const f32x4 w0 = *(const f32x4*)(cw + k * 1024 + chx), w1 = *(const f32x4*)(cw + k * 1024 + chx + 4);
;             a[0] += w0.x * bflo(v.x); a[1] += w0.y * bfhi(v.x); a[2] += w0.z * bflo(v.y); a[3] += w0.w * bfhi(v.y);
;             a[4] += w1.x * bflo(v.z); a[5] += w1.y * bfhi(v.z); a[6] += w1.z * bflo(v.w); a[7] += w1.w * bfhi(v.w); } }
; DI void ssd_p3_item(const Params& p, int L, int item, LAS unsigned char* lds, int tid) {
;     ...
;     for (int i = 0; i < 8; ++i) { const int u = tid + 512 * i, l = u & 127, rest = u >> 7, hx = rest >> 3, ch = (rest & 7) * 8; float o[8];
;         conv8(proj, b, c * 128 + l, (g * 4 + hx) * 64 + ch, cw, cb, o);
.LBB0_436:
	v_add_u32_e32 v40, s5, v141
	v_ashrrev_i32_e32 v115, 10, v40
	v_lshrrev_b32_e32 v40, 4, v40
	v_and_b32_e32 v117, 56, v40
	v_add_u32_e32 v40, s81, v115
	v_lshl_or_b32 v124, v40, 6, v117
	v_ashrrev_i32_e32 v125, 31, v124
	v_lshlrev_b64 v[122:123], 2, v[124:125]
	v_lshl_add_u64 v[44:45], s[52:53], 0, v[122:123]
	global_load_dwordx4 v[40:43], v[44:45], off offset:16
	s_nop 0
	global_load_dwordx4 v[44:47], v[44:45], off
	v_lshl_add_u64 v[122:123], s[24:25], 0, v[122:123]
	s_and_saveexec_b64 s[56:57], s[6:7]
	s_cbranch_execz .LBB0_439
	v_lshl_add_u64 v[126:127], v[124:125], 1, v[106:107]
	global_load_dwordx4 v[126:129], v[126:127], off
	s_nop 0
	global_load_dwordx4 v[130:133], v[122:123], off offset:16
	global_load_dwordx4 v[134:137], v[122:123], off
	s_waitcnt vmcnt(2)
	v_lshlrev_b32_e32 v138, 16, v126
	v_and_b32_e32 v139, 0xffff0000, v126
	v_lshlrev_b32_e32 v126, 16, v127
	v_and_b32_e32 v127, 0xffff0000, v127
	s_waitcnt vmcnt(0)
	v_pk_fma_f32 v[46:47], v[136:137], v[126:127], v[46:47]
	v_lshlrev_b32_e32 v126, 16, v128
	v_and_b32_e32 v127, 0xffff0000, v128
	v_pk_fma_f32 v[40:41], v[130:131], v[126:127], v[40:41]
	v_lshlrev_b32_e32 v126, 16, v129
	v_and_b32_e32 v127, 0xffff0000, v129
	v_pk_fma_f32 v[44:45], v[134:135], v[138:139], v[44:45]
	v_pk_fma_f32 v[42:43], v[132:133], v[126:127], v[42:43]
	s_or_b64 exec, exec, s[56:57]
	s_and_saveexec_b64 s[56:57], s[8:9]
	s_cbranch_execnz .LBB0_440
